# third (FFN2-gu) conversion tail throttled with s_sleep 100 per item to reduce memory contention with the last GEMM round
# speedup vs baseline: 1.0013x; 1.0013x over previous
.Lcv3_la_end:
	s_sleep 100
	s_cmp_eq_u32 s28, 0
	s_cbranch_scc1 .Lcv3_done
	s_cmp_eq_u32 s22, 18
	s_cbranch_scc1 .Lcv3_wb_w18
	s_cmp_eq_u32 s22, 16
	s_cbranch_scc1 .Lcv3_wb_w16
	s_waitcnt vmcnt(8)
	s_branch .Lcv3_wb_wd

.Lcv3_lb_end:
	s_sleep 100
	s_cmp_eq_u32 s22, 0
	s_cbranch_scc1 .Lcv3_done
	s_cmp_eq_u32 s28, 18
	s_cbranch_scc1 .Lcv3_wa_w18
	s_cmp_eq_u32 s28, 16
	s_cbranch_scc1 .Lcv3_wa_w16
	s_waitcnt vmcnt(8)
	s_branch .Lcv3_wa_wd
